# full stack with the step's 8 LDS-DMA issues folded into the QK MFMA stream (one per MFMA) instead of a burst before it
# speedup vs baseline: 1.0115x; 1.0056x over previous
.LBB0_185:
	s_waitcnt vmcnt(0)
	s_barrier
	v_mbcnt_lo_u32_b32 v192, -1, 0
	v_mbcnt_hi_u32_b32 v192, -1, v192
	s_add_i32 s35, 0, 0x10000
	s_add_i32 s37, s35, s61
	s_add_i32 s92, s37, 0x4000
	s_add_i32 s35, s35, s65
	s_add_i32 s93, s35, 0x4000
	s_add_u32 s98, s8, s14
	s_addc_u32 s99, s9, s15
	s_add_u32 s100, s8, s28
	s_addc_u32 s101, s9, s29
	s_add_i32 s36, s68, s79
	s_add_i32 s90, s36, 64
	s_add_i32 s34, s79, 63
	s_mul_hi_i32 s91, s90, 0xa000
	s_mul_i32 s90, s90, 0xa000
	s_add_u32 s90, s82, s90
	s_addc_u32 s91, s83, s91
	s_add_i32 s94, s47, s70
	s_add_i32 s95, s94, 0x380
	s_add_i32 s96, s47, s74
	s_add_i32 s97, s47, s77
	s_addk_i32 s97, 0xff80
	v_ashrrev_i32_e32 v188, 5, v192
	v_and_b32_e32 v193, 31, v192
	v_lshlrev_b32_e32 v189, 4, v192
	v_lshlrev_b32_e32 v191, 4, v188
	v_lshlrev_b32_e32 v190, 8, v193
	v_bitop3_b32 v2, v189, v191, s48 bitop3:0x6c
	v_add3_u32 v6, s84, v2, v190
	v_add_u32_e32 v7, 32, v191
	v_bitop3_b32 v7, v7, v189, s48 bitop3:0x78
	v_add3_u32 v250, s84, v7, v190
	v_add_u32_e32 v7, 64, v191
	v_bitop3_b32 v7, v7, v189, s48 bitop3:0x78
	v_add3_u32 v222, s84, v7, v190
	v_add_u32_e32 v7, 0x60, v191
	v_bitop3_b32 v7, v7, v189, s48 bitop3:0x78
	v_add3_u32 v190, s84, v7, v190
	v_add_u32_e32 v189, s81, v189
	ds_read_b128 v[2:5], v6
	ds_read_b128 v[194:197], v6 offset:8192
	ds_read_b128 v[198:201], v250
	ds_read_b128 v[202:205], v250 offset:8192
	ds_read_b128 v[206:209], v222
	ds_read_b128 v[210:213], v222 offset:8192
	ds_read_b128 v[214:217], v190
	ds_read_b128 v[218:221], v190 offset:8192
	ds_read_b128 v[226:229], v6 offset:128
	ds_read_b128 v[230:233], v6 offset:8320
	s_waitcnt lgkmcnt(9)
	s_mov_b32 m0, s37
	v_mfma_f32_32x32x16_bf16 v[18:33], v[2:5], v[34:37], 0
	global_load_lds_dwordx4 v251, s[98:99]
	s_waitcnt lgkmcnt(8)
	s_mov_b32 m0, s92
	v_mfma_f32_32x32x16_bf16 v[2:17], v[194:197], v[34:37], 0
	global_load_lds_dwordx4 v251, s[100:101]
	ds_read_b128 v[194:197], v250 offset:128
	s_waitcnt lgkmcnt(8)
	s_mov_b32 m0, s35
	v_mfma_f32_32x32x16_bf16 v[18:33], v[198:201], v[38:41], v[18:33]
	global_load_lds_dwordx4 v252, s[98:99]
	ds_read_b128 v[198:201], v250 offset:8320
	s_waitcnt lgkmcnt(8)
	s_mov_b32 m0, s93
	v_mfma_f32_32x32x16_bf16 v[2:17], v[202:205], v[38:41], v[2:17]
	global_load_lds_dwordx4 v252, s[100:101]
	ds_read_b128 v[202:205], v222 offset:128
	s_waitcnt lgkmcnt(8)
	s_mov_b32 m0, s94
	v_mfma_f32_32x32x16_bf16 v[18:33], v[206:209], v[42:45], v[18:33]
	global_load_lds_dwordx4 v253, s[90:91]
	ds_read_b128 v[206:209], v222 offset:8320
	s_waitcnt lgkmcnt(8)
	s_mov_b32 m0, s95
	v_mfma_f32_32x32x16_bf16 v[2:17], v[210:213], v[42:45], v[2:17]
	global_load_lds_dwordx4 v253, s[90:91] offset:128
	ds_read_b128 v[210:213], v190 offset:128
	s_waitcnt lgkmcnt(8)
	s_mov_b32 m0, s96
	v_mfma_f32_32x32x16_bf16 v[18:33], v[214:217], v[46:49], v[18:33]
	global_load_lds_dwordx4 v254, s[90:91]
	ds_read_b128 v[214:217], v190 offset:8320
	s_waitcnt lgkmcnt(8)
	s_mov_b32 m0, s97
	v_mfma_f32_32x32x16_bf16 v[2:17], v[218:221], v[46:49], v[2:17]
	global_load_lds_dwordx4 v254, s[90:91] offset:128
	ds_read_b128 v[218:221], v189
	s_waitcnt lgkmcnt(8)
	v_mfma_f32_32x32x16_bf16 v[18:33], v[226:229], v[50:53], v[18:33]
	ds_read_b128 v[226:229], v189 offset:1024
	s_waitcnt lgkmcnt(8)
	v_mfma_f32_32x32x16_bf16 v[2:17], v[230:233], v[50:53], v[2:17]
	s_waitcnt lgkmcnt(7)
	v_mfma_f32_32x32x16_bf16 v[18:33], v[194:197], v[54:57], v[18:33]
	s_waitcnt lgkmcnt(6)
	v_mfma_f32_32x32x16_bf16 v[2:17], v[198:201], v[54:57], v[2:17]
	s_waitcnt lgkmcnt(1)
	v_mfma_f32_32x32x16_bf16 v[18:33], v[202:205], v[218:221], v[18:33]
	v_mfma_f32_32x32x16_bf16 v[2:17], v[206:209], v[218:221], v[2:17]
	s_waitcnt lgkmcnt(0)
	v_mfma_f32_32x32x16_bf16 v[18:33], v[210:213], v[226:229], v[18:33]
	s_cmp_le_u32 s34, s59
	v_mfma_f32_32x32x16_bf16 v[2:17], v[214:217], v[226:229], v[2:17]
	s_cbranch_scc1 .LBB0_187
	v_lshlrev_b32_e32 v188, 2, v188
	v_sub_u32_e32 v188, v193, v188
	v_add_u32_e32 v188, s86, v188
	v_add_u32_e32 v189, 0x80000001, v188
	v_cmp_gt_u32_e32 vcc, s46, v189
	s_nop 4
	v_cndmask_b32_e32 v18, v225, v18, vcc
	v_cmp_lt_i32_e32 vcc, 31, v189
	s_nop 1
	v_cndmask_b32_e32 v2, v225, v2, vcc
	v_cmp_lt_i32_e32 vcc, 0, v189
	v_subrev_u32_e32 v189, 31, v188
	s_nop 0
	v_cndmask_b32_e32 v19, v225, v19, vcc
	v_cmp_lt_u32_e32 vcc, s49, v189
	v_subrev_u32_e32 v189, 32, v188
	s_nop 0
	v_cndmask_b32_e32 v3, v225, v3, vcc
	v_cmp_lt_u32_e32 vcc, s49, v188
	s_nop 1
	v_cndmask_b32_e32 v20, v225, v20, vcc
	v_cmp_lt_u32_e32 vcc, s49, v189
	v_add_u32_e32 v189, -1, v188
	s_nop 0
	v_cndmask_b32_e32 v4, v225, v4, vcc
	v_cmp_lt_u32_e32 vcc, s49, v189
	v_subrev_u32_e32 v189, 33, v188
	s_nop 0
	v_cndmask_b32_e32 v21, v225, v21, vcc
	v_cmp_lt_u32_e32 vcc, s49, v189
	v_add_u32_e32 v189, -6, v188
	s_nop 0
	v_cndmask_b32_e32 v5, v225, v5, vcc
	v_cmp_lt_u32_e32 vcc, s49, v189
	v_subrev_u32_e32 v189, 38, v188
	s_nop 0
	v_cndmask_b32_e32 v22, v225, v22, vcc
	v_cmp_lt_u32_e32 vcc, s49, v189
	v_add_u32_e32 v189, -7, v188
	s_nop 0
	v_cndmask_b32_e32 v6, v225, v6, vcc
	v_cmp_lt_u32_e32 vcc, s49, v189
	v_subrev_u32_e32 v189, 39, v188
	s_nop 0
	v_cndmask_b32_e32 v23, v225, v23, vcc
	v_cmp_lt_u32_e32 vcc, s49, v189
	v_add_u32_e32 v189, -8, v188
	s_nop 0
	v_cndmask_b32_e32 v7, v225, v7, vcc
	v_cmp_lt_u32_e32 vcc, s49, v189
	v_subrev_u32_e32 v189, 40, v188
	s_nop 0
	v_cndmask_b32_e32 v24, v225, v24, vcc
	v_cmp_lt_u32_e32 vcc, s49, v189
	v_add_u32_e32 v189, -9, v188
	s_nop 0
	v_cndmask_b32_e32 v8, v225, v8, vcc
	v_cmp_lt_u32_e32 vcc, s49, v189
	v_subrev_u32_e32 v189, 41, v188
	s_nop 0
	v_cndmask_b32_e32 v25, v225, v25, vcc
	v_cmp_lt_u32_e32 vcc, s49, v189
	v_add_u32_e32 v189, -14, v188
	s_nop 0
	v_cndmask_b32_e32 v9, v225, v9, vcc
	v_cmp_lt_u32_e32 vcc, s49, v189
	v_subrev_u32_e32 v189, 46, v188
	s_nop 0
	v_cndmask_b32_e32 v26, v225, v26, vcc
	v_cmp_lt_u32_e32 vcc, s49, v189
	v_add_u32_e32 v189, -15, v188
	s_nop 0
	v_cndmask_b32_e32 v10, v225, v10, vcc
	v_cmp_lt_u32_e32 vcc, s49, v189
	v_subrev_u32_e32 v189, 47, v188
	s_nop 0
	v_cndmask_b32_e32 v27, v225, v27, vcc
	v_cmp_lt_u32_e32 vcc, s49, v189
	v_add_u32_e32 v189, -16, v188
	s_nop 0
	v_cndmask_b32_e32 v11, v225, v11, vcc
	v_cmp_lt_u32_e32 vcc, s49, v189
	v_subrev_u32_e32 v189, 48, v188
	s_nop 0
	v_cndmask_b32_e32 v28, v225, v28, vcc
	v_cmp_lt_u32_e32 vcc, s49, v189
	v_subrev_u32_e32 v189, 17, v188
	s_nop 0
	v_cndmask_b32_e32 v12, v225, v12, vcc
	v_cmp_lt_u32_e32 vcc, s49, v189
	v_subrev_u32_e32 v189, 49, v188
	s_nop 0
	v_cndmask_b32_e32 v29, v225, v29, vcc
	v_cmp_lt_u32_e32 vcc, s49, v189
	v_subrev_u32_e32 v189, 22, v188
	s_nop 0
	v_cndmask_b32_e32 v13, v225, v13, vcc
	v_cmp_lt_u32_e32 vcc, s49, v189
	v_subrev_u32_e32 v189, 54, v188
	s_nop 0
	v_cndmask_b32_e32 v30, v225, v30, vcc
	v_cmp_lt_u32_e32 vcc, s49, v189
	v_subrev_u32_e32 v189, 23, v188
	s_nop 0
	v_cndmask_b32_e32 v14, v225, v14, vcc
	v_cmp_lt_u32_e32 vcc, s49, v189
	v_subrev_u32_e32 v189, 55, v188
	s_nop 0
	v_cndmask_b32_e32 v31, v225, v31, vcc
	v_cmp_lt_u32_e32 vcc, s49, v189
	v_subrev_u32_e32 v189, 24, v188
	s_nop 0
	v_cndmask_b32_e32 v15, v225, v15, vcc
	v_cmp_lt_u32_e32 vcc, s49, v189
	v_subrev_u32_e32 v189, 56, v188
	s_nop 0
	v_cndmask_b32_e32 v32, v225, v32, vcc
	v_cmp_lt_u32_e32 vcc, s49, v189
	v_subrev_u32_e32 v189, 25, v188
	v_subrev_u32_e32 v188, 57, v188
	v_cndmask_b32_e32 v16, v225, v16, vcc
	v_cmp_lt_u32_e32 vcc, s49, v189
	s_nop 1
	v_cndmask_b32_e32 v33, v225, v33, vcc
	v_cmp_lt_u32_e32 vcc, s49, v188
	s_nop 1
	v_cndmask_b32_e32 v17, v225, v17, vcc

.LBB0_192:
	s_cmp_lg_u32 0, -1
	s_cselect_b32 s34, 0, 0
	s_add_i32 s34, s34, 0x8000
	s_waitcnt lgkmcnt(0)
	v_add_u32_e32 v220, s34, v255
	v_xor_b32_e32 v221, 0x110, v220
	ds_read_b64_tr_b16 v[18:19], v220 offset:0
	ds_read_b64_tr_b16 v[20:21], v221 offset:0
	v_xor_b32_e32 v222, 32, v220
	ds_read_b64_tr_b16 v[22:23], v222 offset:0
	v_xor_b32_e32 v250, 32, v221
	ds_read_b64_tr_b16 v[24:25], v250 offset:0
	ds_read_b64_tr_b16 v[26:27], v220 offset:0x200
	ds_read_b64_tr_b16 v[28:29], v221 offset:0x200
	s_waitcnt lgkmcnt(4)
	v_permlane16_swap_b32_e32 v10, v14
	v_permlane16_swap_b32_e32 v11, v15
	v_permlane16_swap_b32_e32 v12, v16
	v_permlane16_swap_b32_e32 v13, v17
	v_permlane16_swap_b32_e32 v2, v6
	v_permlane16_swap_b32_e32 v3, v7
	v_permlane16_swap_b32_e32 v4, v8
	v_permlane16_swap_b32_e32 v5, v9
	v_mfma_f32_16x16x32_bf16 v[30:33], v[10:13], v[18:21], v[58:61]
	v_mfma_f32_16x16x32_bf16 v[18:21], v[14:17], v[18:21], v[178:181]
	ds_read_b64_tr_b16 v[58:59], v222 offset:0x200
	ds_read_b64_tr_b16 v[60:61], v250 offset:0x200
	s_waitcnt lgkmcnt(4)
	v_mfma_f32_16x16x32_bf16 v[62:65], v[10:13], v[22:25], v[62:65]
	v_mfma_f32_16x16x32_bf16 v[22:25], v[14:17], v[22:25], v[166:169]
	ds_read_b64_tr_b16 v[166:167], v220 offset:0x400
	ds_read_b64_tr_b16 v[168:169], v221 offset:0x400
	s_waitcnt lgkmcnt(4)
	v_mfma_f32_16x16x32_bf16 v[66:69], v[10:13], v[26:29], v[66:69]
	v_mfma_f32_16x16x32_bf16 v[26:29], v[14:17], v[26:29], v[162:165]
	ds_read_b64_tr_b16 v[162:163], v222 offset:0x400
	ds_read_b64_tr_b16 v[164:165], v250 offset:0x400
	s_waitcnt lgkmcnt(4)
	v_mfma_f32_16x16x32_bf16 v[70:73], v[10:13], v[58:61], v[70:73]
	v_mfma_f32_16x16x32_bf16 v[58:61], v[14:17], v[58:61], v[154:157]
	ds_read_b64_tr_b16 v[154:155], v220 offset:0x600
	ds_read_b64_tr_b16 v[156:157], v221 offset:0x600
	s_waitcnt lgkmcnt(4)
	v_mfma_f32_16x16x32_bf16 v[178:181], v[10:13], v[166:169], v[74:77]
	v_mfma_f32_16x16x32_bf16 v[150:153], v[14:17], v[166:169], v[150:153]
	ds_read_b64_tr_b16 v[74:75], v222 offset:0x600
	ds_read_b64_tr_b16 v[76:77], v250 offset:0x600
	s_waitcnt lgkmcnt(4)
	v_mfma_f32_16x16x32_bf16 v[166:169], v[10:13], v[162:165], v[82:85]
	v_mfma_f32_16x16x32_bf16 v[162:165], v[14:17], v[162:165], v[142:145]
	ds_read_b64_tr_b16 v[82:83], v220 offset:0x2000
	ds_read_b64_tr_b16 v[84:85], v221 offset:0x2000
	s_waitcnt lgkmcnt(4)
	v_mfma_f32_16x16x32_bf16 v[192:195], v[10:13], v[154:157], v[90:93]
	v_mfma_f32_16x16x32_bf16 v[154:157], v[14:17], v[154:157], v[138:141]
	ds_read_b64_tr_b16 v[90:91], v222 offset:0x2000
	ds_read_b64_tr_b16 v[92:93], v250 offset:0x2000
	s_waitcnt lgkmcnt(4)
	v_mfma_f32_16x16x32_bf16 v[196:199], v[10:13], v[74:77], v[98:101]
	v_mfma_f32_16x16x32_bf16 v[200:203], v[14:17], v[74:77], v[130:133]
	ds_read_b64_tr_b16 v[74:75], v220 offset:0x2200
	ds_read_b64_tr_b16 v[76:77], v221 offset:0x2200
	s_waitcnt lgkmcnt(4)
	v_mfma_f32_16x16x32_bf16 v[110:113], v[10:13], v[82:85], v[110:113]
	v_mfma_f32_16x16x32_bf16 v[126:129], v[14:17], v[82:85], v[126:129]
	ds_read_b64_tr_b16 v[82:83], v222 offset:0x2200
	ds_read_b64_tr_b16 v[84:85], v250 offset:0x2200
	s_waitcnt lgkmcnt(4)
	v_mfma_f32_16x16x32_bf16 v[122:125], v[10:13], v[90:93], v[122:125]
	v_mfma_f32_16x16x32_bf16 v[118:121], v[14:17], v[90:93], v[118:121]
	ds_read_b64_tr_b16 v[90:91], v220 offset:0x2400
	ds_read_b64_tr_b16 v[92:93], v221 offset:0x2400
	s_waitcnt lgkmcnt(4)
	v_mfma_f32_16x16x32_bf16 v[204:207], v[10:13], v[74:77], v[134:137]
	v_mfma_f32_16x16x32_bf16 v[208:211], v[14:17], v[74:77], v[114:117]
	ds_read_b64_tr_b16 v[74:75], v222 offset:0x2400
	ds_read_b64_tr_b16 v[76:77], v250 offset:0x2400
	s_waitcnt lgkmcnt(4)
	v_mfma_f32_16x16x32_bf16 v[212:215], v[10:13], v[82:85], v[146:149]
	v_mfma_f32_16x16x32_bf16 v[216:219], v[14:17], v[82:85], v[106:109]
	ds_read_b64_tr_b16 v[82:83], v220 offset:0x2600
	ds_read_b64_tr_b16 v[84:85], v221 offset:0x2600
	s_waitcnt lgkmcnt(4)
	v_mfma_f32_16x16x32_bf16 v[226:229], v[10:13], v[90:93], v[158:161]
	v_mfma_f32_16x16x32_bf16 v[230:233], v[14:17], v[90:93], v[102:105]
	ds_read_b64_tr_b16 v[90:91], v222 offset:0x2600
	ds_read_b64_tr_b16 v[92:93], v250 offset:0x2600
	s_waitcnt lgkmcnt(4)
	v_mfma_f32_16x16x32_bf16 v[234:237], v[10:13], v[74:77], v[174:177]
	v_mfma_f32_16x16x32_bf16 v[238:241], v[14:17], v[74:77], v[94:97]
	ds_read_b64_tr_b16 v[94:95], v220 offset:0x4000
	ds_read_b64_tr_b16 v[96:97], v221 offset:0x4000
	s_waitcnt lgkmcnt(4)
	v_mfma_f32_16x16x32_bf16 v[242:245], v[10:13], v[82:85], v[182:185]
	v_mfma_f32_16x16x32_bf16 v[246:249], v[14:17], v[82:85], v[86:89]
	ds_read_b64_tr_b16 v[82:83], v222 offset:0x4000
	ds_read_b64_tr_b16 v[84:85], v250 offset:0x4000
	s_waitcnt lgkmcnt(4)
	v_mfma_f32_16x16x32_bf16 v[10:13], v[10:13], v[90:93], v[170:173]
	v_mfma_f32_16x16x32_bf16 v[14:17], v[14:17], v[90:93], v[78:81]
	ds_read_b64_tr_b16 v[86:87], v220 offset:0x4200
	ds_read_b64_tr_b16 v[88:89], v221 offset:0x4200
	s_waitcnt lgkmcnt(4)
	v_mfma_f32_16x16x32_bf16 v[74:77], v[2:5], v[94:97], v[30:33]
	v_mfma_f32_16x16x32_bf16 v[130:133], v[6:9], v[94:97], v[18:21]
	ds_read_b64_tr_b16 v[18:19], v222 offset:0x4200
	ds_read_b64_tr_b16 v[20:21], v250 offset:0x4200
	s_waitcnt lgkmcnt(4)
	v_mfma_f32_16x16x32_bf16 v[78:81], v[2:5], v[82:85], v[62:65]
	v_mfma_f32_16x16x32_bf16 v[134:137], v[6:9], v[82:85], v[22:25]
	ds_read_b64_tr_b16 v[22:23], v220 offset:0x4400
	ds_read_b64_tr_b16 v[24:25], v221 offset:0x4400
	s_waitcnt lgkmcnt(4)
	v_mfma_f32_16x16x32_bf16 v[82:85], v[2:5], v[86:89], v[66:69]
	v_mfma_f32_16x16x32_bf16 v[138:141], v[6:9], v[86:89], v[26:29]
	ds_read_b64_tr_b16 v[26:27], v222 offset:0x4400
	ds_read_b64_tr_b16 v[28:29], v250 offset:0x4400
	s_waitcnt lgkmcnt(4)
	v_mfma_f32_16x16x32_bf16 v[86:89], v[2:5], v[18:21], v[70:73]
	v_mfma_f32_16x16x32_bf16 v[142:145], v[6:9], v[18:21], v[58:61]
	ds_read_b64_tr_b16 v[18:19], v220 offset:0x4600
	ds_read_b64_tr_b16 v[20:21], v221 offset:0x4600
	s_waitcnt lgkmcnt(4)
	v_mfma_f32_16x16x32_bf16 v[90:93], v[2:5], v[22:25], v[178:181]
	v_mfma_f32_16x16x32_bf16 v[146:149], v[6:9], v[22:25], v[150:153]
	ds_read_b64_tr_b16 v[22:23], v222 offset:0x4600
	ds_read_b64_tr_b16 v[24:25], v250 offset:0x4600
	s_waitcnt lgkmcnt(4)
	v_mfma_f32_16x16x32_bf16 v[94:97], v[2:5], v[26:29], v[166:169]
	v_mfma_f32_16x16x32_bf16 v[150:153], v[6:9], v[26:29], v[162:165]
	ds_read_b64_tr_b16 v[26:27], v220 offset:0x6000
	ds_read_b64_tr_b16 v[28:29], v221 offset:0x6000
	s_waitcnt lgkmcnt(4)
	v_mfma_f32_16x16x32_bf16 v[98:101], v[2:5], v[18:21], v[192:195]
	v_mfma_f32_16x16x32_bf16 v[154:157], v[6:9], v[18:21], v[154:157]
	ds_read_b64_tr_b16 v[18:19], v222 offset:0x6000
	ds_read_b64_tr_b16 v[20:21], v250 offset:0x6000
	s_waitcnt lgkmcnt(4)
	v_mfma_f32_16x16x32_bf16 v[102:105], v[2:5], v[22:25], v[196:199]
	v_mfma_f32_16x16x32_bf16 v[158:161], v[6:9], v[22:25], v[200:203]
	ds_read_b64_tr_b16 v[22:23], v220 offset:0x6200
	ds_read_b64_tr_b16 v[24:25], v221 offset:0x6200
	s_waitcnt lgkmcnt(4)
	v_mfma_f32_16x16x32_bf16 v[106:109], v[2:5], v[26:29], v[110:113]
	v_mfma_f32_16x16x32_bf16 v[162:165], v[6:9], v[26:29], v[126:129]
	ds_read_b64_tr_b16 v[26:27], v222 offset:0x6200
	ds_read_b64_tr_b16 v[28:29], v250 offset:0x6200
	s_waitcnt lgkmcnt(4)
	v_mfma_f32_16x16x32_bf16 v[110:113], v[2:5], v[18:21], v[122:125]
	v_mfma_f32_16x16x32_bf16 v[166:169], v[6:9], v[18:21], v[118:121]
	ds_read_b64_tr_b16 v[18:19], v220 offset:0x6400
	ds_read_b64_tr_b16 v[20:21], v221 offset:0x6400
	s_waitcnt lgkmcnt(4)
	v_mfma_f32_16x16x32_bf16 v[114:117], v[2:5], v[22:25], v[204:207]
	v_mfma_f32_16x16x32_bf16 v[170:173], v[6:9], v[22:25], v[208:211]
	ds_read_b64_tr_b16 v[22:23], v222 offset:0x6400
	ds_read_b64_tr_b16 v[24:25], v250 offset:0x6400
	s_waitcnt lgkmcnt(4)
	v_mfma_f32_16x16x32_bf16 v[118:121], v[2:5], v[26:29], v[212:215]
	v_mfma_f32_16x16x32_bf16 v[174:177], v[6:9], v[26:29], v[216:219]
	ds_read_b64_tr_b16 v[26:27], v220 offset:0x6600
	ds_read_b64_tr_b16 v[28:29], v221 offset:0x6600
	s_waitcnt lgkmcnt(4)
	v_mfma_f32_16x16x32_bf16 v[122:125], v[2:5], v[18:21], v[226:229]
	v_mfma_f32_16x16x32_bf16 v[178:181], v[6:9], v[18:21], v[230:233]
	ds_read_b64_tr_b16 v[18:19], v222 offset:0x6600
	ds_read_b64_tr_b16 v[20:21], v250 offset:0x6600
	s_waitcnt lgkmcnt(4)
	v_mfma_f32_16x16x32_bf16 v[126:129], v[2:5], v[22:25], v[234:237]
	v_mfma_f32_16x16x32_bf16 v[182:185], v[6:9], v[22:25], v[238:241]
	s_waitcnt lgkmcnt(2)
	v_mfma_f32_16x16x32_bf16 v[66:69], v[2:5], v[26:29], v[242:245]
	v_mfma_f32_16x16x32_bf16 v[70:73], v[6:9], v[26:29], v[246:249]
	s_waitcnt lgkmcnt(0)
	v_mfma_f32_16x16x32_bf16 v[58:61], v[2:5], v[18:21], v[10:13]
	v_mfma_f32_16x16x32_bf16 v[62:65], v[6:9], v[18:21], v[14:17]
	s_cmp_ge_u32 s89, s80
	s_waitcnt vmcnt(0)
	s_barrier
	s_cselect_b64 s[34:35], -1, 0
	s_and_b64 vcc, exec, s[34:35]
	v_mbcnt_lo_u32_b32 v192, -1, 0
	v_mbcnt_hi_u32_b32 v192, -1, v192
	s_cbranch_vccnz .LBB0_194
	s_add_u32 s98, s8, s30
	s_addc_u32 s99, s9, s31
	s_addk_i32 s36, 0x80
	s_mul_hi_i32 s37, s36, 0xa000
	s_mul_i32 s36, s36, 0xa000
	s_add_u32 s36, s82, s36
	s_addc_u32 s37, s83, s37
	s_add_i32 s100, s72, 0xffffff80
	s_add_i32 s101, s78, 0xffffff80
	v_ashrrev_i32_e32 v193, 5, v192
	v_and_b32_e32 v194, 31, v192
	v_lshlrev_b32_e32 v195, 4, v192
	v_lshlrev_b32_e32 v221, 4, v193
	v_lshlrev_b32_e32 v220, 8, v194
	v_bitop3_b32 v2, v195, v221, s48 bitop3:0x6c
	v_add3_u32 v6, s85, v2, v220
	v_add_u32_e32 v7, 32, v221
	v_bitop3_b32 v7, v7, v195, s48 bitop3:0x78
	v_add3_u32 v250, s85, v7, v220
	v_add_u32_e32 v7, 64, v221
	v_bitop3_b32 v7, v7, v195, s48 bitop3:0x78
	v_add3_u32 v222, s85, v7, v220
	v_add_u32_e32 v7, 0x60, v221
	v_bitop3_b32 v7, v7, v195, s48 bitop3:0x78
	v_add3_u32 v220, s85, v7, v220
	v_add_u32_e32 v195, s81, v195
	ds_read_b128 v[2:5], v6
	ds_read_b128 v[196:199], v6 offset:8192
	ds_read_b128 v[200:203], v250
	ds_read_b128 v[204:207], v250 offset:8192
	ds_read_b128 v[208:211], v222
	ds_read_b128 v[212:215], v222 offset:8192
	ds_read_b128 v[216:219], v220
	ds_read_b128 v[226:229], v220 offset:8192
	ds_read_b128 v[230:233], v6 offset:128
	ds_read_b128 v[234:237], v6 offset:8320
	s_waitcnt lgkmcnt(9)
	s_mov_b32 m0, s62
	v_mfma_f32_32x32x16_bf16 v[18:33], v[2:5], v[34:37], 0
	global_load_lds_dwordx4 v251, s[98:99]
	s_waitcnt lgkmcnt(8)
	s_mov_b32 m0, s63
	v_mfma_f32_32x32x16_bf16 v[2:17], v[196:199], v[34:37], 0
	global_load_lds_dwordx4 v251, s[8:9]
	ds_read_b128 v[196:199], v250 offset:128
	s_waitcnt lgkmcnt(8)
	s_mov_b32 m0, s66
	v_mfma_f32_32x32x16_bf16 v[18:33], v[200:203], v[38:41], v[18:33]
	global_load_lds_dwordx4 v252, s[98:99]
	ds_read_b128 v[200:203], v250 offset:8320
	s_waitcnt lgkmcnt(8)
	s_mov_b32 m0, s67
	v_mfma_f32_32x32x16_bf16 v[2:17], v[204:207], v[38:41], v[2:17]
	global_load_lds_dwordx4 v252, s[8:9]
	ds_read_b128 v[204:207], v222 offset:128
	s_waitcnt lgkmcnt(8)
	s_mov_b32 m0, s71
	v_mfma_f32_32x32x16_bf16 v[18:33], v[208:211], v[42:45], v[18:33]
	global_load_lds_dwordx4 v253, s[36:37]
	ds_read_b128 v[208:211], v222 offset:8320
	s_waitcnt lgkmcnt(8)
	s_mov_b32 m0, s100
	v_mfma_f32_32x32x16_bf16 v[2:17], v[212:215], v[42:45], v[2:17]
	global_load_lds_dwordx4 v253, s[36:37] offset:128
	ds_read_b128 v[212:215], v220 offset:128
	s_waitcnt lgkmcnt(8)
	s_mov_b32 m0, s75
	v_mfma_f32_32x32x16_bf16 v[18:33], v[216:219], v[46:49], v[18:33]
	global_load_lds_dwordx4 v254, s[36:37]
	ds_read_b128 v[216:219], v220 offset:8320
	s_waitcnt lgkmcnt(8)
	s_mov_b32 m0, s101
	v_mfma_f32_32x32x16_bf16 v[2:17], v[226:229], v[46:49], v[2:17]
	global_load_lds_dwordx4 v254, s[36:37] offset:128
	ds_read_b128 v[226:229], v195
	s_waitcnt lgkmcnt(8)
	v_mfma_f32_32x32x16_bf16 v[18:33], v[230:233], v[50:53], v[18:33]
	ds_read_b128 v[230:233], v195 offset:1024
	s_waitcnt lgkmcnt(8)
	v_mfma_f32_32x32x16_bf16 v[2:17], v[234:237], v[50:53], v[2:17]
	s_waitcnt lgkmcnt(7)
	v_mfma_f32_32x32x16_bf16 v[18:33], v[196:199], v[54:57], v[18:33]
	s_waitcnt lgkmcnt(6)
	v_mfma_f32_32x32x16_bf16 v[2:17], v[200:203], v[54:57], v[2:17]
	s_waitcnt lgkmcnt(1)
	v_mfma_f32_32x32x16_bf16 v[18:33], v[204:207], v[226:229], v[18:33]
	v_mfma_f32_32x32x16_bf16 v[2:17], v[208:211], v[226:229], v[2:17]
	s_waitcnt lgkmcnt(0)
	v_mfma_f32_32x32x16_bf16 v[18:33], v[212:215], v[230:233], v[18:33]
	s_add_i32 s36, s79, 0x7f
	s_cmp_le_u32 s36, s59
	v_mfma_f32_32x32x16_bf16 v[2:17], v[216:219], v[230:233], v[2:17]
	s_branch .Lqk1_join

.Lqk1_join:
	s_cbranch_scc1 .LBB0_196
	v_lshlrev_b32_e32 v193, 2, v193
	v_sub_u32_e32 v193, v194, v193
	v_add_u32_e32 v193, s86, v193
	v_add_u32_e32 v195, 0x7fffffc1, v193
	v_cmp_gt_u32_e32 vcc, s46, v195
	s_nop 4
	v_cndmask_b32_e32 v18, v225, v18, vcc
	v_cmp_lt_i32_e32 vcc, 31, v195
	s_nop 1
	v_cndmask_b32_e32 v2, v225, v2, vcc
	v_cmp_lt_i32_e32 vcc, 0, v195
	v_add_u32_e32 v195, 0xffffffa1, v193
	s_nop 0
	v_cndmask_b32_e32 v19, v225, v19, vcc
	v_cmp_lt_u32_e32 vcc, s49, v195
	v_subrev_u32_e32 v195, 64, v193
	s_nop 0
	v_cndmask_b32_e32 v3, v225, v3, vcc
	v_cmp_lt_u32_e32 vcc, s49, v195
	v_add_u32_e32 v195, 0xffffffa0, v193
	s_nop 0
	v_cndmask_b32_e32 v20, v225, v20, vcc
	v_cmp_lt_u32_e32 vcc, s49, v195
	v_add_u32_e32 v195, 0xffffffbf, v193
	s_nop 0
	v_cndmask_b32_e32 v4, v225, v4, vcc
	v_cmp_lt_u32_e32 vcc, s49, v195
	v_add_u32_e32 v195, 0xffffff9f, v193
	s_nop 0
	v_cndmask_b32_e32 v21, v225, v21, vcc
	v_cmp_lt_u32_e32 vcc, s49, v195
	v_add_u32_e32 v195, 0xffffffba, v193
	s_nop 0
	v_cndmask_b32_e32 v5, v225, v5, vcc
	v_cmp_lt_u32_e32 vcc, s49, v195
	v_add_u32_e32 v195, 0xffffff9a, v193
	s_nop 0
	v_cndmask_b32_e32 v22, v225, v22, vcc
	v_cmp_lt_u32_e32 vcc, s49, v195
	v_add_u32_e32 v195, 0xffffffb9, v193
	s_nop 0
	v_cndmask_b32_e32 v6, v225, v6, vcc
	v_cmp_lt_u32_e32 vcc, s49, v195
	v_add_u32_e32 v195, 0xffffff99, v193
	s_nop 0
	v_cndmask_b32_e32 v23, v225, v23, vcc
	v_cmp_lt_u32_e32 vcc, s49, v195
	v_add_u32_e32 v195, 0xffffffb8, v193
	s_nop 0
	v_cndmask_b32_e32 v7, v225, v7, vcc
	v_cmp_lt_u32_e32 vcc, s49, v195
	v_add_u32_e32 v195, 0xffffff98, v193
	s_nop 0
	v_cndmask_b32_e32 v24, v225, v24, vcc
	v_cmp_lt_u32_e32 vcc, s49, v195
	v_add_u32_e32 v195, 0xffffffb7, v193
	s_nop 0
	v_cndmask_b32_e32 v8, v225, v8, vcc
	v_cmp_lt_u32_e32 vcc, s49, v195
	v_add_u32_e32 v195, 0xffffff97, v193
	s_nop 0
	v_cndmask_b32_e32 v25, v225, v25, vcc
	v_cmp_lt_u32_e32 vcc, s49, v195
	v_add_u32_e32 v195, 0xffffffb2, v193
	s_nop 0
	v_cndmask_b32_e32 v9, v225, v9, vcc
	v_cmp_lt_u32_e32 vcc, s49, v195
	v_add_u32_e32 v195, 0xffffff92, v193
	s_nop 0
	v_cndmask_b32_e32 v26, v225, v26, vcc
	v_cmp_lt_u32_e32 vcc, s49, v195
	v_add_u32_e32 v195, 0xffffffb1, v193
	s_nop 0
	v_cndmask_b32_e32 v10, v225, v10, vcc
	v_cmp_lt_u32_e32 vcc, s49, v195
	v_add_u32_e32 v195, 0xffffff91, v193
	s_nop 0
	v_cndmask_b32_e32 v27, v225, v27, vcc
	v_cmp_lt_u32_e32 vcc, s49, v195
	v_add_u32_e32 v195, 0xffffffb0, v193
	s_nop 0
	v_cndmask_b32_e32 v11, v225, v11, vcc
	v_cmp_lt_u32_e32 vcc, s49, v195
	v_add_u32_e32 v195, 0xffffff90, v193
	s_nop 0
	v_cndmask_b32_e32 v28, v225, v28, vcc
	v_cmp_lt_u32_e32 vcc, s49, v195
	v_add_u32_e32 v195, 0xffffffaf, v193
	s_nop 0
	v_cndmask_b32_e32 v12, v225, v12, vcc
	v_cmp_lt_u32_e32 vcc, s49, v195
	v_add_u32_e32 v195, 0xffffff8f, v193
	s_nop 0
	v_cndmask_b32_e32 v29, v225, v29, vcc
	v_cmp_lt_u32_e32 vcc, s49, v195
	v_add_u32_e32 v195, 0xffffffaa, v193
	s_nop 0
	v_cndmask_b32_e32 v13, v225, v13, vcc
	v_cmp_lt_u32_e32 vcc, s49, v195
	v_add_u32_e32 v195, 0xffffff8a, v193
	s_nop 0
	v_cndmask_b32_e32 v30, v225, v30, vcc
	v_cmp_lt_u32_e32 vcc, s49, v195
	v_add_u32_e32 v195, 0xffffffa9, v193
	s_nop 0
	v_cndmask_b32_e32 v14, v225, v14, vcc
	v_cmp_lt_u32_e32 vcc, s49, v195
	v_add_u32_e32 v195, 0xffffff89, v193
	s_nop 0
	v_cndmask_b32_e32 v31, v225, v31, vcc
	v_cmp_lt_u32_e32 vcc, s49, v195
	v_add_u32_e32 v195, 0xffffffa8, v193
	s_nop 0
	v_cndmask_b32_e32 v15, v225, v15, vcc
	v_cmp_lt_u32_e32 vcc, s49, v195
	v_add_u32_e32 v195, 0xffffff88, v193
	s_nop 0
	v_cndmask_b32_e32 v32, v225, v32, vcc
	v_cmp_lt_u32_e32 vcc, s49, v195
	v_add_u32_e32 v195, 0xffffffa7, v193
	v_add_u32_e32 v193, 0xffffff87, v193
	v_cndmask_b32_e32 v16, v225, v16, vcc
	v_cmp_lt_u32_e32 vcc, s49, v195
	s_nop 1
	v_cndmask_b32_e32 v33, v225, v33, vcc
	v_cmp_lt_u32_e32 vcc, s49, v193
	s_nop 1
	v_cndmask_b32_e32 v17, v225, v17, vcc
